# scan chains: counted vmcnt at the chunk-loop tops (previous chunk's output stores stay in flight), full wait moved to the one-time prologue
# baseline (speedup 1.0000x reference)
; DI int crow(int r, int h) { return (r & 3) + 8 * (r >> 2) + 4 * h; }
; DI unsigned char* launder_ptr(unsigned char* q) { asm volatile("" : "+s"(q)); return q; }
; DI int opaque_tid() { int t = threadIdx.x; asm volatile("" : "+v"(t)); return t; }
; DI void stream_of(int n, int cpc, int& m, int& T, int& soff) { if (n < cpc) { m = n; T = CTX; soff = 0; } else { m = n - cpc; T = SEQ; soff = CTX; } }
; DI void hg_scan_block(const Params& p, int chain_in, unsigned char* smem) {
;   int chain = blockIdx.x; asm volatile("" : "+v"(chain)); chain = __builtin_amdgcn_readfirstlane(chain) - chain_in;
;   unsigned char* const WS_ = launder_ptr(p.ws);
;   const int tid = opaque_tid(), lane = tid & 63, sl = tid >> 6, l31 = lane & 31, h = lane >> 5;
;   const int hd = chain & 3, b = (chain >> 2) & 3, dir = chain >> 4;
;   float* OHG = (float*)(WS_ + O_OHG) + (size_t)dir * NTOK * 512;
;   bfr* sU = (bfr*)smem;
;   const bfr *s_qhat = sU, *s_khT = sU + 4096, *s_vT = sU + 8192;
;   float* s_ds = (float*)(smem + 24576);
;   const u32x4* src = (const u32x4*)(WS_ + O_HGU) + (size_t)chain * 136 * 1536;
;   const float* dsg = (const float*)(WS_ + O_HGD) + (size_t)chain * 136 * 128;
;   u32x4 st[6]; float dsr;
; #pragma unroll
;   for (int i = 0; i < 6; ++i) st[i] = src[tid + 256 * i];
;   dsr = dsg[tid & 127];
;   float oc[16];
;   {
;     int m0_, T0_, so0_; stream_of(0, 8, m0_, T0_, so0_);
; #pragma unroll
;     for (int r = 0; r < 16; ++r) {
;       const int pos = 32 * m0_ + crow(r, h), t = dir ? T0_ - 1 - pos : pos;
;       oc[r] = OHG[(size_t)(b * SP + so0_ + t) * 512 + hd * 128 + 32 * sl + l31];
.LBB0_494:
	s_or_b64 exec, exec, s[4:5]
	v_readlane_b32 s6, v255, 1
	v_readlane_b32 s7, v255, 2
	v_mov_b32_e32 v211, v216
	s_mov_b64 s[4:5], -1
	s_and_b64 vcc, exec, s[6:7]
	s_mov_b32 s37, 0x800000
	s_barrier
	s_cbranch_vccz .LBB0_505
	v_readlane_b32 s4, v255, 35
	v_readlane_b32 s5, v255, 36
	s_andn2_b64 vcc, exec, s[4:5]
	s_cbranch_vccnz .LBB0_504
	v_lshrrev_b32_e32 v165, 6, v216
	v_lshlrev_b32_e32 v165, 10, v165
	s_nop 0
	v_readfirstlane_b32 s38, v165
	s_mov_b32 s39, 0x8000
	v_readlane_b32 s4, v254, 28
	s_nop 1
	v_mov_b32_e32 v0, s4
	s_mov_b64 s[4:5], s[84:85]
	v_readfirstlane_b32 s8, v0
	s_sub_i32 s9, s8, 32
	s_ashr_i32 s6, s9, 4
	s_mul_hi_i32 s10, s6, 0x2200000
	s_mul_i32 s11, s6, 0x2200000
	s_mul_i32 s6, s9, 0x330000
	v_mov_b32_e32 v0, v216
	s_mul_hi_i32 s7, s9, 0x330000
	s_add_u32 s6, s4, s6
	s_addc_u32 s7, s5, s7
	v_ashrrev_i32_e32 v1, 31, v0
	v_lshl_add_u64 v[104:105], v[0:1], 4, s[6:7]
	s_mov_b32 s6, 0x619cf000
	v_add_co_u32_e32 v2, vcc, s6, v104
	s_mov_b32 s6, 0x619d0000
	s_nop 0
	v_addc_co_u32_e32 v3, vcc, 0, v105, vcc
	v_add_co_u32_e32 v4, vcc, s6, v104
	s_mov_b32 s6, 0x619d1000
	s_nop 0
	v_addc_co_u32_e32 v5, vcc, 0, v105, vcc
	v_add_u32_e32 v164, 0x0, v165
	v_add_co_u32_e32 v162, vcc, 0x600, v2
	v_readfirstlane_b32 s28, v164
	s_nop 0
	v_addc_co_u32_e32 v163, vcc, 0, v3, vcc
	s_mov_b32 m0, s28
	s_nop 0
	global_load_lds_dwordx4 v[162:163], off
	v_add_u32_e32 v164, 0x1000, v165
	v_add_co_u32_e32 v162, vcc, 0x600, v4
	v_readfirstlane_b32 s28, v164
	s_nop 0
	v_addc_co_u32_e32 v163, vcc, 0, v5, vcc
	s_mov_b32 m0, s28
	s_nop 0
	global_load_lds_dwordx4 v[162:163], off
	v_add_co_u32_e32 v2, vcc, s6, v104
	s_mov_b32 s6, 0x619d2000
	s_nop 0
	v_addc_co_u32_e32 v3, vcc, 0, v105, vcc
	v_add_co_u32_e32 v4, vcc, s6, v104
	s_mov_b32 s6, 0x619d3000
	s_nop 0
	v_addc_co_u32_e32 v5, vcc, 0, v105, vcc
	v_add_u32_e32 v164, 0x2000, v165
	v_add_co_u32_e32 v162, vcc, 0x600, v2
	v_readfirstlane_b32 s28, v164
	s_nop 0
	v_addc_co_u32_e32 v163, vcc, 0, v3, vcc
	s_mov_b32 m0, s28
	s_nop 0
	global_load_lds_dwordx4 v[162:163], off
	v_add_u32_e32 v164, 0x3000, v165
	v_add_co_u32_e32 v162, vcc, 0x600, v4
	v_readfirstlane_b32 s28, v164
	s_nop 0
	v_addc_co_u32_e32 v163, vcc, 0, v5, vcc
	s_mov_b32 m0, s28
	s_nop 0
	global_load_lds_dwordx4 v[162:163], off
	v_add_co_u32_e32 v2, vcc, s6, v104
	s_bfe_u32 s22, s8, 0x20002
	s_nop 0
	v_addc_co_u32_e32 v3, vcc, 0, v105, vcc
	s_mov_b32 s6, 0x619d4000
	s_add_u32 s11, s4, s11
	s_mul_i32 s21, s9, 0x11000
	v_add_co_u32_e32 v4, vcc, s6, v104
	s_addc_u32 s10, s5, s10
	s_mul_hi_i32 s20, s9, 0x11000
	v_addc_co_u32_e32 v5, vcc, 0, v105, vcc
	v_add_u32_e32 v164, 0x4000, v165
	v_add_co_u32_e32 v162, vcc, 0x600, v2
	v_readfirstlane_b32 s28, v164
	s_nop 0
	v_addc_co_u32_e32 v163, vcc, 0, v3, vcc
	s_mov_b32 m0, s28
	s_nop 0
	global_load_lds_dwordx4 v[162:163], off
	v_add_u32_e32 v164, 0x5000, v165
	v_add_co_u32_e32 v162, vcc, 0x600, v4
	v_readfirstlane_b32 s28, v164
	s_nop 0
	v_addc_co_u32_e32 v163, vcc, 0, v5, vcc
	s_mov_b32 m0, s28
	s_nop 0
	global_load_lds_dwordx4 v[162:163], off
	v_and_b32_e32 v2, 0x7f, v0
	s_add_u32 s4, s4, s21
	v_lshlrev_b32_e32 v208, 2, v2
	s_addc_u32 s5, s5, s20
	v_lshl_add_u64 v[2:3], s[4:5], 0, v[208:209]
	s_mov_b32 s4, 0x67fcf000
	s_cmp_lt_u32 s9, 16
	v_bfe_u32 v21, v0, 5, 1
	v_add_co_u32_e32 v4, vcc, s4, v2
	s_cselect_b64 s[6:7], -1, 0
	s_lshl_b32 s4, s8, 9
	v_ashrrev_i32_e32 v20, 6, v0
	v_lshlrev_b32_e32 v110, 2, v21
	s_and_b32 s4, s4, 0x600
	v_and_b32_e32 v1, 31, v0
	v_xor_b32_e32 v8, 0xff, v110
	v_lshlrev_b32_e32 v6, 5, v20
	s_add_u32 s4, s11, s4
	s_mul_i32 s20, s22, 0x1100
	v_ashrrev_i32_e32 v7, 31, v6
	s_addc_u32 s5, s10, 0
	s_add_u32 s30, s4, 0x681ef600
	s_addc_u32 s31, s5, 0
	v_lshlrev_b32_e32 v208, 2, v1
	v_cndmask_b32_e64 v1, v8, v110, s[6:7]
	v_lshl_add_u64 v[6:7], v[6:7], 2, s[4:5]
	v_or_b32_e32 v1, s20, v1
	v_lshl_add_u64 v[6:7], v[6:7], 0, v[208:209]
	v_lshlrev_b32_e32 v208, 11, v1
	v_or_b32_e32 v1, 1, v110
	v_xor_b32_e32 v8, 0xfe, v110
	s_mov_b64 s[4:5], 0x681ef600
	v_cndmask_b32_e64 v1, v8, v1, s[6:7]
	v_lshl_add_u64 v[106:107], v[6:7], 0, s[4:5]
	v_lshrrev_b32_e32 v160, 6, v216
	v_and_b32_e32 v162, 31, v216
	v_lshlrev_b32_e32 v160, 7, v160
	v_lshlrev_b32_e32 v163, 11, v110
	v_lshl_or_b32 v160, v162, 2, v160
	v_sub_u32_e32 v162, 0xf800, v163
	v_mov_b32_e32 v161, 0x800
	v_cndmask_b32_e64 v163, v162, v163, s[6:7]
	v_mov_b32_e32 v162, 0xfffff800
	v_add_u32_e32 v160, v160, v163
	v_cndmask_b32_e64 v161, v162, v161, s[6:7]
	v_or_b32_e32 v1, s20, v1
	v_lshl_add_u64 v[6:7], v[106:107], 0, v[208:209]
	v_lshlrev_b32_e32 v208, 11, v1
	v_or_b32_e32 v1, 2, v110
	v_xor_b32_e32 v10, 0xfd, v110
	v_cndmask_b32_e64 v1, v10, v1, s[6:7]
	v_or_b32_e32 v1, s20, v1
	v_lshl_add_u64 v[8:9], v[106:107], 0, v[208:209]
	v_lshlrev_b32_e32 v208, 11, v1
	v_or_b32_e32 v1, 3, v110
	v_xor_b32_e32 v12, 0xfc, v110
	v_cndmask_b32_e64 v1, v12, v1, s[6:7]
	v_or_b32_e32 v1, s20, v1
	v_lshl_add_u64 v[10:11], v[106:107], 0, v[208:209]
	v_lshlrev_b32_e32 v208, 11, v1
	v_or_b32_e32 v1, 8, v110
	v_xor_b32_e32 v14, 0xf7, v110
; DI int crow(int r, int h) { return (r & 3) + 8 * (r >> 2) + 4 * h; }
; DI f32x16 zero16() { f32x16 z; for (int i = 0; i < 16; ++i) z[i] = 0.f; return z; }
; DI void stream_of(int n, int cpc, int& m, int& T, int& soff) { if (n < cpc) { m = n; T = CTX; soff = 0; } else { m = n - cpc; T = SEQ; soff = CTX; } }
; DI void hg_scan_block(const Params& p, int chain_in, unsigned char* smem) {
;     ...
;   const u32x4* src = (const u32x4*)(WS_ + O_HGU) + (size_t)chain * 136 * 1536;
;   const float* dsg = (const float*)(WS_ + O_HGD) + (size_t)chain * 136 * 128;
;   u32x4 st[6]; float dsr;
; #pragma unroll
;   for (int i = 0; i < 6; ++i) st[i] = src[tid + 256 * i];
;   dsr = dsg[tid & 127];
;   float oc[16];
;   {
;     int m0_, T0_, so0_; stream_of(0, 8, m0_, T0_, so0_);
; #pragma unroll
;     for (int r = 0; r < 16; ++r) {
;       const int pos = 32 * m0_ + crow(r, h), t = dir ? T0_ - 1 - pos : pos;
;       oc[r] = OHG[(size_t)(b * SP + so0_ + t) * 512 + hd * 128 + 32 * sl + l31];
;     }
;   }
;   f32x16 S[4];
;   for (int i = 0; i < 4; ++i) S[i] = zero16();
	v_cndmask_b32_e64 v1, v14, v1, s[6:7]
	v_or_b32_e32 v1, s20, v1
	v_lshl_add_u64 v[12:13], v[106:107], 0, v[208:209]
	v_lshlrev_b32_e32 v208, 11, v1
	v_or_b32_e32 v1, 9, v110
	v_xor_b32_e32 v16, 0xf6, v110
	v_cndmask_b32_e64 v1, v16, v1, s[6:7]
	v_or_b32_e32 v1, s20, v1
	v_lshl_add_u64 v[14:15], v[106:107], 0, v[208:209]
	v_lshlrev_b32_e32 v208, 11, v1
	v_or_b32_e32 v1, 10, v110
	v_xor_b32_e32 v18, 0xf5, v110
	v_cndmask_b32_e64 v1, v18, v1, s[6:7]
	v_or_b32_e32 v1, s20, v1
	v_addc_co_u32_e32 v5, vcc, 0, v3, vcc
	v_lshl_add_u64 v[16:17], v[106:107], 0, v[208:209]
	v_lshlrev_b32_e32 v208, 11, v1
	v_lshl_add_u64 v[18:19], v[106:107], 0, v[208:209]
	global_load_dword v111, v[4:5], off offset:1536
	global_load_dword v148, v[6:7], off
	global_load_dword v147, v[8:9], off
	global_load_dword v144, v[10:11], off
	global_load_dword v142, v[12:13], off
	global_load_dword v140, v[14:15], off
	global_load_dword v138, v[16:17], off
	global_load_dword v137, v[18:19], off
	v_or_b32_e32 v1, 11, v110
	v_xor_b32_e32 v4, 0xf4, v110
	v_cndmask_b32_e64 v1, v4, v1, s[6:7]
	v_or_b32_e32 v1, s20, v1
	v_lshlrev_b32_e32 v208, 11, v1
	v_or_b32_e32 v1, 16, v110
	v_xor_b32_e32 v6, 0xef, v110
	v_cndmask_b32_e64 v1, v6, v1, s[6:7]
	v_or_b32_e32 v1, s20, v1
	v_lshl_add_u64 v[4:5], v[106:107], 0, v[208:209]
	v_lshlrev_b32_e32 v208, 11, v1
	v_or_b32_e32 v1, 17, v110
	v_xor_b32_e32 v8, 0xee, v110
	v_cndmask_b32_e64 v1, v8, v1, s[6:7]
	v_or_b32_e32 v1, s20, v1
	v_lshl_add_u64 v[6:7], v[106:107], 0, v[208:209]
	v_lshlrev_b32_e32 v208, 11, v1
	v_or_b32_e32 v1, 18, v110
	v_xor_b32_e32 v10, 0xed, v110
	v_cndmask_b32_e64 v1, v10, v1, s[6:7]
	v_or_b32_e32 v1, s20, v1
	v_lshl_add_u64 v[8:9], v[106:107], 0, v[208:209]
	v_lshlrev_b32_e32 v208, 11, v1
	v_or_b32_e32 v1, 19, v110
	v_xor_b32_e32 v12, 0xec, v110
	v_cndmask_b32_e64 v1, v12, v1, s[6:7]
	v_or_b32_e32 v1, s20, v1
	v_lshl_add_u64 v[10:11], v[106:107], 0, v[208:209]
	v_lshlrev_b32_e32 v208, 11, v1
	v_or_b32_e32 v1, 24, v110
	v_xor_b32_e32 v14, 0xe7, v110
	v_cndmask_b32_e64 v1, v14, v1, s[6:7]
	v_or_b32_e32 v1, s20, v1
	v_lshl_add_u64 v[12:13], v[106:107], 0, v[208:209]
	v_lshlrev_b32_e32 v208, 11, v1
	v_or_b32_e32 v1, 25, v110
	v_xor_b32_e32 v16, 0xe6, v110
	v_cndmask_b32_e64 v1, v16, v1, s[6:7]
	v_or_b32_e32 v1, s20, v1
	v_lshl_add_u64 v[14:15], v[106:107], 0, v[208:209]
	v_lshlrev_b32_e32 v208, 11, v1
	v_or_b32_e32 v1, 26, v110
	v_xor_b32_e32 v18, 0xe5, v110
	v_cndmask_b32_e64 v1, v18, v1, s[6:7]
	v_or_b32_e32 v1, s20, v1
	v_lshl_add_u64 v[16:17], v[106:107], 0, v[208:209]
	v_lshlrev_b32_e32 v208, 11, v1
	v_lshl_add_u64 v[18:19], v[106:107], 0, v[208:209]
	global_load_dword v146, v[4:5], off
	global_load_dword v145, v[6:7], off
	global_load_dword v143, v[8:9], off
	global_load_dword v141, v[10:11], off
	global_load_dword v139, v[12:13], off
	global_load_dword v136, v[14:15], off
	global_load_dword v135, v[16:17], off
	global_load_dword v133, v[18:19], off
	v_or_b32_e32 v1, 27, v110
	v_xor_b32_e32 v4, 0xe4, v110
	v_cndmask_b32_e64 v1, v4, v1, s[6:7]
	v_or_b32_e32 v1, s20, v1
	v_lshlrev_b32_e32 v208, 11, v1
	v_lshl_add_u64 v[4:5], v[106:107], 0, v[208:209]
	global_load_dword v132, v[4:5], off
	v_and_b32_e32 v1, 63, v0
	s_movk_i32 s4, 0x80
	v_lshlrev_b32_e32 v112, 4, v0
	v_cmp_gt_i32_e64 s[4:5], s4, v0
	v_lshlrev_b32_e32 v113, 4, v1
	v_mul_lo_u32 v1, v0, -12
	s_mov_b64 s[8:9], 0x67fcf800
	v_mov_b32_e32 v0, 0
	s_mov_b32 s21, 0
	v_lshl_or_b32 v114, v20, 11, v113
	v_lshlrev_b32_e32 v115, 4, v21
	v_lshl_add_u64 v[108:109], v[2:3], 0, s[8:9]
	s_mov_b64 s[8:9], 0
	v_add_u32_e32 v116, v112, v1
	v_mov_b32_e32 v1, v0
	v_mov_b32_e32 v2, v0
	v_mov_b32_e32 v3, v0
	v_mov_b32_e32 v4, v0
	v_mov_b32_e32 v5, v0
	v_mov_b32_e32 v6, v0
	v_mov_b32_e32 v7, v0
	v_mov_b32_e32 v8, v0
	v_mov_b32_e32 v9, v0
	v_mov_b32_e32 v10, v0
	v_mov_b32_e32 v11, v0
	v_mov_b32_e32 v12, v0
	v_mov_b32_e32 v13, v0
	v_mov_b32_e32 v14, v0
	v_mov_b32_e32 v15, v0
	v_mov_b32_e32 v16, v0
	v_mov_b32_e32 v17, v0
	v_mov_b32_e32 v18, v0
	v_mov_b32_e32 v19, v0
	v_mov_b32_e32 v20, v0
	v_mov_b32_e32 v21, v0
	v_mov_b32_e32 v22, v0
	v_mov_b32_e32 v23, v0
	v_mov_b32_e32 v24, v0
	v_mov_b32_e32 v25, v0
	v_mov_b32_e32 v26, v0
	v_mov_b32_e32 v27, v0
	v_mov_b32_e32 v28, v0
	v_mov_b32_e32 v29, v0
	v_mov_b32_e32 v30, v0
	v_mov_b32_e32 v31, v0
	v_mov_b32_e32 v32, v0
	v_mov_b32_e32 v33, v0
	v_mov_b32_e32 v34, v0
	v_mov_b32_e32 v35, v0
	v_mov_b32_e32 v36, v0
	v_mov_b32_e32 v37, v0
	v_mov_b32_e32 v38, v0
	v_mov_b32_e32 v39, v0
	v_mov_b32_e32 v40, v0
	v_mov_b32_e32 v41, v0
	v_mov_b32_e32 v42, v0
	v_mov_b32_e32 v43, v0
	v_mov_b32_e32 v44, v0
	v_mov_b32_e32 v45, v0
	v_mov_b32_e32 v46, v0
	v_mov_b32_e32 v47, v0
	v_mov_b32_e32 v48, v0
	v_mov_b32_e32 v49, v0
	v_mov_b32_e32 v50, v0
	v_mov_b32_e32 v51, v0
	v_mov_b32_e32 v52, v0
	v_mov_b32_e32 v53, v0
	v_mov_b32_e32 v54, v0
	v_mov_b32_e32 v55, v0
	v_mov_b32_e32 v56, v0
	v_mov_b32_e32 v57, v0
	v_mov_b32_e32 v58, v0
	v_mov_b32_e32 v59, v0
	v_mov_b32_e32 v60, v0
	v_mov_b32_e32 v61, v0
	v_mov_b32_e32 v62, v0
	v_mov_b32_e32 v63, v0
	s_waitcnt vmcnt(0)
	s_branch .LBB0_498

; DI void hg_scan_block(const Params& p, int chain_in, unsigned char* smem) {
;     ...
; #pragma unroll 1
;   for (int n = 0; n < 136; ++n) {
;     __syncthreads();
; #pragma unroll
;     for (int i = 0; i < 6; ++i) ((u32x4*)sU)[tid + 256 * i] = st[i];
;     if (tid < 128) s_ds[tid] = dsr;
;     __syncthreads();
;     if (n + 1 < 136) {
; #pragma unroll
;       for (int i = 0; i < 6; ++i) st[i] = src[(size_t)(n + 1) * 1536 + tid + 256 * i];
;       dsr = dsg[(size_t)(n + 1) * 128 + (tid & 127)];
;     }
.LBB0_498:
	s_waitcnt vmcnt(16)
	s_and_saveexec_b64 s[10:11], s[4:5]
	ds_write_b32 v116, v111 offset:24576
	s_or_b64 exec, exec, s[10:11]
	s_cmp_lg_u32 s8, 0x32a000
	s_cselect_b64 s[10:11], -1, 0
	s_cmp_eq_u32 s8, 0x32a000
	s_waitcnt lgkmcnt(0)
	s_barrier
	s_cbranch_scc1 .LBB0_502
	v_lshl_add_u64 v[64:65], v[104:105], 0, s[8:9]
	s_add_i32 s29, s39, s38
	s_xor_b32 s39, s39, 0x8000
	s_mov_b32 s28, s29
	v_add_co_u32_e32 v66, vcc, 0x619d5600, v64
	s_mov_b32 m0, s28
	s_nop 0
	v_addc_co_u32_e32 v67, vcc, 0, v65, vcc
	global_load_lds_dwordx4 v[66:67], off
	s_add_i32 s28, s29, 0x1000
	v_add_co_u32_e32 v66, vcc, 0x619d6600, v64
	s_mov_b32 m0, s28
	s_nop 0
	v_addc_co_u32_e32 v67, vcc, 0, v65, vcc
	global_load_lds_dwordx4 v[66:67], off
	s_add_i32 s28, s29, 0x2000
	v_add_co_u32_e32 v66, vcc, 0x619d7600, v64
	s_mov_b32 m0, s28
	s_nop 0
	v_addc_co_u32_e32 v67, vcc, 0, v65, vcc
	global_load_lds_dwordx4 v[66:67], off
	s_add_i32 s28, s29, 0x3000
	v_add_co_u32_e32 v66, vcc, 0x619d8600, v64
	s_mov_b32 m0, s28
	s_nop 0
	v_addc_co_u32_e32 v67, vcc, 0, v65, vcc
	global_load_lds_dwordx4 v[66:67], off
	s_add_i32 s28, s29, 0x4000
	v_add_co_u32_e32 v66, vcc, 0x619d9600, v64
	s_mov_b32 m0, s28
	s_nop 0
	v_addc_co_u32_e32 v67, vcc, 0, v65, vcc
	global_load_lds_dwordx4 v[66:67], off
	s_add_i32 s28, s29, 0x5000
	v_add_co_u32_e32 v66, vcc, 0x619da600, v64
	s_mov_b32 m0, s28
	s_nop 0
	v_addc_co_u32_e32 v67, vcc, 0, v65, vcc
	global_load_lds_dwordx4 v[66:67], off
	global_load_dword v111, v[108:109], off

; DI unsigned char* launder_ptr(unsigned char* q) { asm volatile("" : "+s"(q)); return q; }
; DI int opaque_tid() { int t = threadIdx.x; asm volatile("" : "+v"(t)); return t; }
; DI f32x16 zero16() { f32x16 z; for (int i = 0; i < 16; ++i) z[i] = 0.f; return z; }
; DI void dn_scan_block(const Params& p, int chain_in, unsigned char* smem) {
;   int chain = blockIdx.x; asm volatile("" : "+v"(chain)); chain = __builtin_amdgcn_readfirstlane(chain) - chain_in;
;   unsigned char* const WS_ = launder_ptr(p.ws);
;   const int tid = opaque_tid(), lane = tid & 63, sl = tid >> 6, l31 = lane & 31, h = lane >> 5;
;   const int hd = chain & 3, b = (chain >> 2) & 3, dir = chain >> 4;
;   float* ODN = (float*)(WS_ + O_ODN) + (size_t)dir * NTOK * 512;
;   const float* GL = (const float*)(WS_ + O_DNG);
;   bfr* sU = (bfr*)smem;
;   const bfr *s_wneg = sU, *s_qdec = sU + 8192, *s_kdT = sU + 16384, *s_aqk = sU + 24576, *s_u = sU + 28672;
;   const u32x4* src = (const u32x4*)(WS_ + O_DNU) + (size_t)chain * 68 * 4608;
;   u32x4 st[18];
; #pragma unroll
;   for (int i = 0; i < 18; ++i) st[i] = src[tid + 256 * i];
;   f32x16 S[4];
;   for (int i = 0; i < 4; ++i) S[i] = zero16();
.LBB0_505:
	s_andn2_b64 vcc, exec, s[4:5]
	s_cbranch_vccnz .LBB0_510
	v_readlane_b32 s4, v254, 28
	s_mov_b32 s8, 0
	s_nop 5
	v_mov_b32_e32 v0, s4
	s_mov_b64 s[4:5], s[84:85]
	v_readfirstlane_b32 s21, v0
	s_ashr_i32 s6, s21, 4
	s_mul_hi_i32 s7, s6, 0x2200000
	s_mul_i32 s6, s6, 0x2200000
	s_add_u32 s22, s4, s6
	s_addc_u32 s23, s5, s7
	s_mul_i32 s6, s21, 0x4c8000
	v_mov_b32_e32 v0, v216
	s_mul_hi_i32 s7, s21, 0x4c8000
	s_add_u32 s6, s4, s6
	s_addc_u32 s7, s5, s7
	v_ashrrev_i32_e32 v1, 31, v0
	v_lshl_add_u64 v[212:213], v[0:1], 4, s[6:7]
	s_mov_b32 s6, 0x53ccd000
	v_add_co_u32_e32 v2, vcc, s6, v212
	s_mov_b32 s6, 0x53cce000
	s_nop 0
	v_addc_co_u32_e32 v3, vcc, 0, v213, vcc
	v_add_co_u32_e32 v4, vcc, s6, v212
	s_mov_b32 s6, 0x53ccf000
	s_nop 0
	v_addc_co_u32_e32 v5, vcc, 0, v213, vcc
	global_load_dwordx4 v[96:99], v[2:3], off offset:1024
	global_load_dwordx4 v[100:103], v[4:5], off offset:1024
	v_add_co_u32_e32 v2, vcc, s6, v212
	s_mov_b32 s6, 0x53cd0000
	s_nop 0
	v_addc_co_u32_e32 v3, vcc, 0, v213, vcc
	v_add_co_u32_e32 v4, vcc, s6, v212
	s_mov_b32 s6, 0x53cd1000
	s_nop 0
	v_addc_co_u32_e32 v5, vcc, 0, v213, vcc
	global_load_dwordx4 v[104:107], v[2:3], off offset:1024
	global_load_dwordx4 v[108:111], v[4:5], off offset:1024
	v_add_co_u32_e32 v2, vcc, s6, v212
	s_mov_b32 s6, 0x53cd2000
	s_nop 0
	v_addc_co_u32_e32 v3, vcc, 0, v213, vcc
	v_add_co_u32_e32 v4, vcc, s6, v212
	s_mov_b32 s6, 0x53cd3000
	s_nop 0
	v_addc_co_u32_e32 v5, vcc, 0, v213, vcc
	global_load_dwordx4 v[112:115], v[2:3], off offset:1024
	global_load_dwordx4 v[116:119], v[4:5], off offset:1024
	v_add_co_u32_e32 v2, vcc, s6, v212
	s_mov_b32 s6, 0x53cd4000
	s_nop 0
	v_addc_co_u32_e32 v3, vcc, 0, v213, vcc
	v_add_co_u32_e32 v4, vcc, s6, v212
	s_mov_b32 s6, 0x53cd5000
	s_nop 0
	v_addc_co_u32_e32 v5, vcc, 0, v213, vcc
	global_load_dwordx4 v[120:123], v[2:3], off offset:1024
	global_load_dwordx4 v[124:127], v[4:5], off offset:1024
	v_add_co_u32_e32 v2, vcc, s6, v212
	s_mov_b32 s6, 0x53cd6000
	s_nop 0
	v_addc_co_u32_e32 v3, vcc, 0, v213, vcc
	v_add_co_u32_e32 v4, vcc, s6, v212
	s_mov_b32 s6, 0x53cd7000
	s_nop 0
	v_addc_co_u32_e32 v5, vcc, 0, v213, vcc
	global_load_dwordx4 v[128:131], v[2:3], off offset:1024
	global_load_dwordx4 v[132:135], v[4:5], off offset:1024
	v_add_co_u32_e32 v2, vcc, s6, v212
	s_mov_b32 s6, 0x53cd8000
	s_nop 0
	v_addc_co_u32_e32 v3, vcc, 0, v213, vcc
	v_add_co_u32_e32 v4, vcc, s6, v212
	s_mov_b32 s6, 0x53cd9000
	s_nop 0
	v_addc_co_u32_e32 v5, vcc, 0, v213, vcc
	global_load_dwordx4 v[136:139], v[2:3], off offset:1024
	global_load_dwordx4 v[140:143], v[4:5], off offset:1024
	v_add_co_u32_e32 v2, vcc, s6, v212
	s_mov_b32 s6, 0x53cda000
	s_nop 0
	v_addc_co_u32_e32 v3, vcc, 0, v213, vcc
	v_add_co_u32_e32 v4, vcc, s6, v212
	s_mov_b32 s6, 0x53cdb000
	s_nop 0
	v_addc_co_u32_e32 v5, vcc, 0, v213, vcc
	global_load_dwordx4 v[144:147], v[2:3], off offset:1024
	global_load_dwordx4 v[148:151], v[4:5], off offset:1024
	v_add_co_u32_e32 v2, vcc, s6, v212
	s_mov_b32 s6, 0x53cdc000
	s_nop 0
	v_addc_co_u32_e32 v3, vcc, 0, v213, vcc
	v_add_co_u32_e32 v4, vcc, s6, v212
	s_mov_b32 s6, 0x53cdd000
	s_nop 0
	v_addc_co_u32_e32 v5, vcc, 0, v213, vcc
	global_load_dwordx4 v[152:155], v[2:3], off offset:1024
	global_load_dwordx4 v[156:159], v[4:5], off offset:1024
	v_add_co_u32_e32 v2, vcc, s6, v212
	s_mov_b32 s6, 0x53cde000
	s_nop 0
	v_addc_co_u32_e32 v3, vcc, 0, v213, vcc
	v_add_co_u32_e32 v4, vcc, s6, v212
	s_bfe_u32 s20, s21, 0x20002
	s_nop 0
	v_addc_co_u32_e32 v5, vcc, 0, v213, vcc
	global_load_dwordx4 v[160:163], v[2:3], off offset:1024
	global_load_dwordx4 v[164:167], v[4:5], off offset:1024
	s_add_u32 s9, s4, 0x5d5cd400
	s_addc_u32 s10, s5, 0
	s_cmp_lt_u32 s21, 16
	s_cselect_b64 s[4:5], -1, 0
	s_lshl_b32 s6, s21, 9
	v_ashrrev_i32_e32 v6, 6, v0
	v_and_b32_e32 v1, 63, v0
	v_and_b32_e32 v2, 31, v0
	v_lshlrev_b32_e32 v223, 4, v0
	v_lshrrev_b32_e32 v0, 3, v0
	s_and_b32 s6, s6, 0x600
	v_lshlrev_b32_e32 v3, 5, v1
	v_lshlrev_b32_e32 v1, 4, v1
	v_and_b32_e32 v225, 4, v0
	v_lshlrev_b32_e32 v0, 5, v6
	s_add_u32 s6, s22, s6
	v_sub_u32_e32 v224, v3, v1
	v_ashrrev_i32_e32 v1, 31, v0
	s_addc_u32 s7, s23, 0
	s_add_u32 s30, s6, 0x5d5cf600
	s_addc_u32 s31, s7, 0
	v_lshl_add_u64 v[0:1], v[0:1], 2, s[6:7]
	v_lshlrev_b32_e32 v208, 2, v2
	v_lshl_add_u64 v[0:1], v[0:1], 0, v[208:209]
	s_mov_b64 s[6:7], 0x5d5cf600
	v_lshl_add_u64 v[214:215], v[0:1], 0, s[6:7]
	v_lshrrev_b32_e32 v230, 6, v216
	v_and_b32_e32 v233, 31, v216
	v_lshlrev_b32_e32 v230, 7, v230
	v_lshlrev_b32_e32 v238, 11, v225
	v_lshl_or_b32 v230, v233, 2, v230
	v_sub_u32_e32 v233, 0xf800, v238
	v_mov_b32_e32 v232, 0x800
	v_cndmask_b32_e64 v238, v233, v238, s[4:5]
	v_mov_b32_e32 v233, 0xfffff800
	v_add_u32_e32 v230, v230, v238
	v_cndmask_b32_e64 v232, v233, v232, s[4:5]
	v_lshl_or_b32 v226, v6, 11, v3
	v_mov_b32_e32 v0, 0
	s_mul_i32 s11, s21, 0x44
	s_mulk_i32 s20, 0x1100
	v_add_u32_e32 v227, 0xe000, v226
	v_or_b32_e32 v228, 1, v225
	v_or_b32_e32 v229, 2, v225
	v_or_b32_e32 v231, 3, v225
	v_or_b32_e32 v235, 8, v225
	v_or_b32_e32 v236, 9, v225
	v_or_b32_e32 v245, 10, v225
	v_or_b32_e32 v246, 11, v225
	v_or_b32_e32 v247, 16, v225
	v_or_b32_e32 v248, 17, v225
	v_or_b32_e32 v249, 18, v225
	v_or_b32_e32 v250, 19, v225
	v_or_b32_e32 v251, 24, v225
	v_or_b32_e32 v252, 25, v225
	v_or_b32_e32 v253, 26, v225
	v_or_b32_e32 v237, 27, v225
	s_mov_b64 s[6:7], 0
	v_mov_b32_e32 v1, v0
	v_mov_b32_e32 v2, v0
	v_mov_b32_e32 v3, v0
	v_mov_b32_e32 v4, v0
	v_mov_b32_e32 v5, v0
	v_mov_b32_e32 v6, v0
	v_mov_b32_e32 v7, v0
	v_mov_b32_e32 v8, v0
	v_mov_b32_e32 v9, v0
	v_mov_b32_e32 v10, v0
	v_mov_b32_e32 v11, v0
	v_mov_b32_e32 v12, v0
	v_mov_b32_e32 v13, v0
	v_mov_b32_e32 v14, v0
	v_mov_b32_e32 v15, v0
	v_mov_b32_e32 v16, v0
	v_mov_b32_e32 v17, v0
	v_mov_b32_e32 v18, v0
	v_mov_b32_e32 v19, v0
	v_mov_b32_e32 v20, v0
	v_mov_b32_e32 v21, v0
	v_mov_b32_e32 v22, v0
	v_mov_b32_e32 v23, v0
	v_mov_b32_e32 v24, v0
	v_mov_b32_e32 v25, v0
	v_mov_b32_e32 v26, v0
	v_mov_b32_e32 v27, v0
	v_mov_b32_e32 v28, v0
	v_mov_b32_e32 v29, v0
	v_mov_b32_e32 v30, v0
	v_mov_b32_e32 v31, v0
	v_mov_b32_e32 v32, v0
	v_mov_b32_e32 v33, v0
	v_mov_b32_e32 v34, v0
	v_mov_b32_e32 v35, v0
	v_mov_b32_e32 v36, v0
	v_mov_b32_e32 v37, v0
	v_mov_b32_e32 v38, v0
	v_mov_b32_e32 v39, v0
	v_mov_b32_e32 v40, v0
	v_mov_b32_e32 v41, v0
	v_mov_b32_e32 v42, v0
	v_mov_b32_e32 v43, v0
	v_mov_b32_e32 v44, v0
	v_mov_b32_e32 v45, v0
	v_mov_b32_e32 v46, v0
	v_mov_b32_e32 v47, v0
	v_mov_b32_e32 v48, v0
	v_mov_b32_e32 v49, v0
	v_mov_b32_e32 v50, v0
	v_mov_b32_e32 v51, v0
	v_mov_b32_e32 v52, v0
	v_mov_b32_e32 v53, v0
	v_mov_b32_e32 v54, v0
	v_mov_b32_e32 v55, v0
	v_mov_b32_e32 v56, v0
	v_mov_b32_e32 v57, v0
	v_mov_b32_e32 v58, v0
	v_mov_b32_e32 v59, v0
	v_mov_b32_e32 v60, v0
	v_mov_b32_e32 v61, v0
	v_mov_b32_e32 v62, v0
	v_mov_b32_e32 v63, v0
	s_waitcnt vmcnt(0)
	s_branch .LBB0_508

; DI void dn_scan_block(const Params& p, int chain_in, unsigned char* smem) {
;     ...
;   for (int n = 0; n < 68; ++n) {
;     __syncthreads();
; #pragma unroll
;     for (int i = 0; i < 18; ++i) ((u32x4*)sU)[tid + 256 * i] = st[i];
;     __syncthreads();
;     if (n + 1 < 68) {
; #pragma unroll
;       for (int i = 0; i < 18; ++i) st[i] = src[(size_t)(n + 1) * 4608 + tid + 256 * i];
;     }
.LBB0_508:
	v_add_u32_e32 v64, 0x10000, v223
	s_waitcnt lgkmcnt(0)
	s_barrier
	s_waitcnt vmcnt(32)
	s_add_i32 s22, s11, s8
	s_ashr_i32 s23, s22, 31
	s_lshl_b64 s[22:23], s[22:23], 2
	s_add_u32 s22, s9, s22
	s_addc_u32 s23, s10, s23
	s_nop 0
	global_load_dword v208, v209, s[22:23]
	ds_write_b128 v223, v[96:99]
	ds_write_b128 v223, v[100:103] offset:4096
	ds_write_b128 v223, v[104:107] offset:8192
	ds_write_b128 v223, v[108:111] offset:12288
	ds_write_b128 v223, v[112:115] offset:16384
	ds_write_b128 v223, v[116:119] offset:20480
	ds_write_b128 v223, v[120:123] offset:24576
	ds_write_b128 v223, v[124:127] offset:28672
	ds_write_b128 v223, v[128:131] offset:32768
	ds_write_b128 v223, v[132:135] offset:36864
	ds_write_b128 v223, v[136:139] offset:40960
	ds_write_b128 v223, v[140:143] offset:45056
	ds_write_b128 v223, v[144:147] offset:49152
	ds_write_b128 v223, v[148:151] offset:53248
	ds_write_b128 v223, v[152:155] offset:57344
	ds_write_b128 v223, v[156:159] offset:61440
	ds_write_b128 v64, v[160:163]
	v_add_u32_e32 v64, 0x11000, v223
	s_cmp_eq_u32 s6, 0x4b6000
	ds_write_b128 v64, v[164:167]
	s_waitcnt lgkmcnt(0)
	s_barrier
	s_waitcnt vmcnt(0)
	s_cbranch_scc1 .LBB0_507
	v_lshl_add_u64 v[64:65], v[212:213], 0, s[6:7]
	v_add_co_u32_e32 v66, vcc, 0x53cdf000, v64
	s_nop 1
	v_addc_co_u32_e32 v67, vcc, 0, v65, vcc
	v_add_co_u32_e32 v68, vcc, 0x53ce0000, v64
	s_nop 1
	v_addc_co_u32_e32 v69, vcc, 0, v65, vcc
	global_load_dwordx4 v[96:99], v[66:67], off offset:1024
	global_load_dwordx4 v[100:103], v[68:69], off offset:1024
	v_add_co_u32_e32 v66, vcc, 0x53ce1000, v64
	s_nop 1
	v_addc_co_u32_e32 v67, vcc, 0, v65, vcc
	v_add_co_u32_e32 v68, vcc, 0x53ce2000, v64
	s_nop 1
	v_addc_co_u32_e32 v69, vcc, 0, v65, vcc
	global_load_dwordx4 v[104:107], v[66:67], off offset:1024
	global_load_dwordx4 v[108:111], v[68:69], off offset:1024
	v_add_co_u32_e32 v66, vcc, 0x53ce3000, v64
	s_nop 1
	v_addc_co_u32_e32 v67, vcc, 0, v65, vcc
	v_add_co_u32_e32 v68, vcc, 0x53ce4000, v64
	s_nop 1
	v_addc_co_u32_e32 v69, vcc, 0, v65, vcc
	global_load_dwordx4 v[112:115], v[66:67], off offset:1024
	global_load_dwordx4 v[116:119], v[68:69], off offset:1024
	v_add_co_u32_e32 v66, vcc, 0x53ce5000, v64
	s_nop 1
	v_addc_co_u32_e32 v67, vcc, 0, v65, vcc
	v_add_co_u32_e32 v68, vcc, 0x53ce6000, v64
	s_nop 1
	v_addc_co_u32_e32 v69, vcc, 0, v65, vcc
	global_load_dwordx4 v[120:123], v[66:67], off offset:1024
	global_load_dwordx4 v[124:127], v[68:69], off offset:1024
	v_add_co_u32_e32 v66, vcc, 0x53ce7000, v64
	s_nop 1
	v_addc_co_u32_e32 v67, vcc, 0, v65, vcc
	v_add_co_u32_e32 v68, vcc, 0x53ce8000, v64
	s_nop 1
	v_addc_co_u32_e32 v69, vcc, 0, v65, vcc
	global_load_dwordx4 v[128:131], v[66:67], off offset:1024
	global_load_dwordx4 v[132:135], v[68:69], off offset:1024
	v_add_co_u32_e32 v66, vcc, 0x53ce9000, v64
	s_nop 1
	v_addc_co_u32_e32 v67, vcc, 0, v65, vcc
	v_add_co_u32_e32 v68, vcc, 0x53cea000, v64
	s_nop 1
	v_addc_co_u32_e32 v69, vcc, 0, v65, vcc
	global_load_dwordx4 v[136:139], v[66:67], off offset:1024
	global_load_dwordx4 v[140:143], v[68:69], off offset:1024
	v_add_co_u32_e32 v66, vcc, 0x53ceb000, v64
	s_nop 1
	v_addc_co_u32_e32 v67, vcc, 0, v65, vcc
	v_add_co_u32_e32 v68, vcc, 0x53cec000, v64
	s_nop 1
	v_addc_co_u32_e32 v69, vcc, 0, v65, vcc
	global_load_dwordx4 v[144:147], v[66:67], off offset:1024
	global_load_dwordx4 v[148:151], v[68:69], off offset:1024
	v_add_co_u32_e32 v66, vcc, 0x53ced000, v64
	s_nop 1
	v_addc_co_u32_e32 v67, vcc, 0, v65, vcc
	v_add_co_u32_e32 v68, vcc, 0x53cee000, v64
	s_nop 1
	v_addc_co_u32_e32 v69, vcc, 0, v65, vcc
	global_load_dwordx4 v[152:155], v[66:67], off offset:1024
	global_load_dwordx4 v[156:159], v[68:69], off offset:1024
	v_add_co_u32_e32 v66, vcc, 0x53cef000, v64
	s_nop 1
	v_addc_co_u32_e32 v67, vcc, 0, v65, vcc
	v_add_co_u32_e32 v64, vcc, 0x53cf0000, v64
	s_nop 1
	v_addc_co_u32_e32 v65, vcc, 0, v65, vcc
	global_load_dwordx4 v[160:163], v[66:67], off offset:1024
	global_load_dwordx4 v[164:167], v[64:65], off offset:1024
	s_branch .LBB0_507
